# DSA top-256 select rewritten by hand: batched LDS loads, per-lane VALU counting with DPP reduce, scalar loop control, writelane mask build
# speedup vs baseline: 1.0495x; 1.0495x over previous
.LBB0_386:
	v_readlane_b32 s0, v252, 27
	s_add_i32 s78, s94, s0
	v_readlane_b32 s0, v252, 41
	v_cmp_ge_i32_e32 vcc, s78, v94
	v_mov_b32_e32 v64, 0
	v_lshl_add_u32 v1, v94, 2, s0
	v_mov_b32_e32 v65, 0
	s_waitcnt lgkmcnt(0)
	s_barrier
	v_writelane_b32 v254, s82, 42
	v_writelane_b32 v254, s83, 43
	v_writelane_b32 v254, s86, 44
	v_writelane_b32 v254, s87, 45
	v_writelane_b32 v254, s94, 46
	v_writelane_b32 v254, s95, 47
	s_mov_b32 s38, 0
	v_readlane_b32 s9, v254, 41
	s_nop 1
	v_writelane_b32 v253, s9, 41
.Lsel_q:
	s_cmp_eq_u32 s38, 0
	s_cbranch_scc0 .Lsel_cfg1
	v_readlane_b32 s8, v252, 27
	v_readlane_b32 s4, v252, 41
	s_branch .Lsel_cfg
.Lsel_cfg1:
	v_readlane_b32 s8, v252, 42
	v_readlane_b32 s4, v252, 43
.Lsel_cfg:
	s_add_i32 s8, s8, s94
	s_lshr_b32 s16, s8, 9
	s_nop 0
	v_lshl_add_u32 v0, v94, 2, s4
	ds_read_b32 v32, v0
	ds_read_b32 v33, v0 offset:256
	ds_read_b32 v34, v0 offset:512
	ds_read_b32 v35, v0 offset:768
	ds_read_b32 v36, v0 offset:1024
	ds_read_b32 v37, v0 offset:1280
	ds_read_b32 v38, v0 offset:1536
	ds_read_b32 v39, v0 offset:1792
	s_waitcnt lgkmcnt(0)
	s_cmp_lt_u32 s16, 1
	s_cbranch_scc1 .Lsel_c0
	ds_read_b32 v40, v0 offset:2048
	ds_read_b32 v41, v0 offset:2304
	ds_read_b32 v42, v0 offset:2560
	ds_read_b32 v43, v0 offset:2816
	ds_read_b32 v44, v0 offset:3072
	ds_read_b32 v45, v0 offset:3328
	ds_read_b32 v46, v0 offset:3584
	ds_read_b32 v47, v0 offset:3840
.Lsel_c0:
	s_sub_i32 s17, s8, 0
	s_sub_i32 s18, s8, 64
	v_add_f32_e32 v32, 0, v32
	v_add_f32_e32 v33, 0, v33
	v_ashrrev_i32_e32 v4, 31, v32
	v_ashrrev_i32_e32 v5, 31, v33
	v_or_b32_e32 v4, 0x80000000, v4
	v_or_b32_e32 v5, 0x80000000, v5
	v_xor_b32_e32 v32, v32, v4
	v_xor_b32_e32 v33, v33, v5
	v_cmp_ge_i32_e64 s[20:21], s17, v94
	v_cmp_ge_i32_e64 s[22:23], s18, v94
	s_nop 0
	v_cndmask_b32_e64 v32, 0, v32, s[20:21]
	v_cndmask_b32_e64 v33, 0, v33, s[22:23]
	s_sub_i32 s17, s8, 128
	s_sub_i32 s18, s8, 192
	v_add_f32_e32 v34, 0, v34
	v_add_f32_e32 v35, 0, v35
	v_ashrrev_i32_e32 v4, 31, v34
	v_ashrrev_i32_e32 v5, 31, v35
	v_or_b32_e32 v4, 0x80000000, v4
	v_or_b32_e32 v5, 0x80000000, v5
	v_xor_b32_e32 v34, v34, v4
	v_xor_b32_e32 v35, v35, v5
	v_cmp_ge_i32_e64 s[20:21], s17, v94
	v_cmp_ge_i32_e64 s[22:23], s18, v94
	s_nop 0
	v_cndmask_b32_e64 v34, 0, v34, s[20:21]
	v_cndmask_b32_e64 v35, 0, v35, s[22:23]
	s_sub_i32 s17, s8, 256
	s_sub_i32 s18, s8, 320
	v_add_f32_e32 v36, 0, v36
	v_add_f32_e32 v37, 0, v37
	v_ashrrev_i32_e32 v4, 31, v36
	v_ashrrev_i32_e32 v5, 31, v37
	v_or_b32_e32 v4, 0x80000000, v4
	v_or_b32_e32 v5, 0x80000000, v5
	v_xor_b32_e32 v36, v36, v4
	v_xor_b32_e32 v37, v37, v5
	v_cmp_ge_i32_e64 s[20:21], s17, v94
	v_cmp_ge_i32_e64 s[22:23], s18, v94
	s_nop 0
	v_cndmask_b32_e64 v36, 0, v36, s[20:21]
	v_cndmask_b32_e64 v37, 0, v37, s[22:23]
	s_sub_i32 s17, s8, 384
	s_sub_i32 s18, s8, 448
	v_add_f32_e32 v38, 0, v38
	v_add_f32_e32 v39, 0, v39
	v_ashrrev_i32_e32 v4, 31, v38
	v_ashrrev_i32_e32 v5, 31, v39
	v_or_b32_e32 v4, 0x80000000, v4
	v_or_b32_e32 v5, 0x80000000, v5
	v_xor_b32_e32 v38, v38, v4
	v_xor_b32_e32 v39, v39, v5
	v_cmp_ge_i32_e64 s[20:21], s17, v94
	v_cmp_ge_i32_e64 s[22:23], s18, v94
	s_nop 0
	v_cndmask_b32_e64 v38, 0, v38, s[20:21]
	v_cndmask_b32_e64 v39, 0, v39, s[22:23]
	s_cmp_lt_u32 s16, 1
	s_cbranch_scc1 .Lsel_loaded
	s_waitcnt lgkmcnt(0)
	s_cmp_lt_u32 s16, 2
	s_cbranch_scc1 .Lsel_c1
	ds_read_b32 v48, v0 offset:4096
	ds_read_b32 v49, v0 offset:4352
	ds_read_b32 v50, v0 offset:4608
	ds_read_b32 v51, v0 offset:4864
	ds_read_b32 v52, v0 offset:5120
	ds_read_b32 v53, v0 offset:5376
	ds_read_b32 v54, v0 offset:5632
	ds_read_b32 v55, v0 offset:5888
.Lsel_c1:
	s_sub_i32 s17, s8, 512
	s_sub_i32 s18, s8, 576
	v_add_f32_e32 v40, 0, v40
	v_add_f32_e32 v41, 0, v41
	v_ashrrev_i32_e32 v4, 31, v40
	v_ashrrev_i32_e32 v5, 31, v41
	v_or_b32_e32 v4, 0x80000000, v4
	v_or_b32_e32 v5, 0x80000000, v5
	v_xor_b32_e32 v40, v40, v4
	v_xor_b32_e32 v41, v41, v5
	v_cmp_ge_i32_e64 s[20:21], s17, v94
	v_cmp_ge_i32_e64 s[22:23], s18, v94
	s_nop 0
	v_cndmask_b32_e64 v40, 0, v40, s[20:21]
	v_cndmask_b32_e64 v41, 0, v41, s[22:23]
	s_sub_i32 s17, s8, 640
	s_sub_i32 s18, s8, 704
	v_add_f32_e32 v42, 0, v42
	v_add_f32_e32 v43, 0, v43
	v_ashrrev_i32_e32 v4, 31, v42
	v_ashrrev_i32_e32 v5, 31, v43
	v_or_b32_e32 v4, 0x80000000, v4
	v_or_b32_e32 v5, 0x80000000, v5
	v_xor_b32_e32 v42, v42, v4
	v_xor_b32_e32 v43, v43, v5
	v_cmp_ge_i32_e64 s[20:21], s17, v94
	v_cmp_ge_i32_e64 s[22:23], s18, v94
	s_nop 0
	v_cndmask_b32_e64 v42, 0, v42, s[20:21]
	v_cndmask_b32_e64 v43, 0, v43, s[22:23]
	s_sub_i32 s17, s8, 768
	s_sub_i32 s18, s8, 832
	v_add_f32_e32 v44, 0, v44
	v_add_f32_e32 v45, 0, v45
	v_ashrrev_i32_e32 v4, 31, v44
	v_ashrrev_i32_e32 v5, 31, v45
	v_or_b32_e32 v4, 0x80000000, v4
	v_or_b32_e32 v5, 0x80000000, v5
	v_xor_b32_e32 v44, v44, v4
	v_xor_b32_e32 v45, v45, v5
	v_cmp_ge_i32_e64 s[20:21], s17, v94
	v_cmp_ge_i32_e64 s[22:23], s18, v94
	s_nop 0
	v_cndmask_b32_e64 v44, 0, v44, s[20:21]
	v_cndmask_b32_e64 v45, 0, v45, s[22:23]
	s_sub_i32 s17, s8, 896
	s_sub_i32 s18, s8, 960
	v_add_f32_e32 v46, 0, v46
	v_add_f32_e32 v47, 0, v47
	v_ashrrev_i32_e32 v4, 31, v46
	v_ashrrev_i32_e32 v5, 31, v47
	v_or_b32_e32 v4, 0x80000000, v4
	v_or_b32_e32 v5, 0x80000000, v5
	v_xor_b32_e32 v46, v46, v4
	v_xor_b32_e32 v47, v47, v5
	v_cmp_ge_i32_e64 s[20:21], s17, v94
	v_cmp_ge_i32_e64 s[22:23], s18, v94
	s_nop 0
	v_cndmask_b32_e64 v46, 0, v46, s[20:21]
	v_cndmask_b32_e64 v47, 0, v47, s[22:23]
	s_cmp_lt_u32 s16, 2
	s_cbranch_scc1 .Lsel_loaded
	s_waitcnt lgkmcnt(0)
	s_cmp_lt_u32 s16, 3
	s_cbranch_scc1 .Lsel_c2
	ds_read_b32 v56, v0 offset:6144
	ds_read_b32 v57, v0 offset:6400
	ds_read_b32 v58, v0 offset:6656
	ds_read_b32 v59, v0 offset:6912
	ds_read_b32 v60, v0 offset:7168
	ds_read_b32 v61, v0 offset:7424
	ds_read_b32 v62, v0 offset:7680
	ds_read_b32 v63, v0 offset:7936
.Lsel_c2:
	s_sub_i32 s17, s8, 1024
	s_sub_i32 s18, s8, 1088
	v_add_f32_e32 v48, 0, v48
	v_add_f32_e32 v49, 0, v49
	v_ashrrev_i32_e32 v4, 31, v48
	v_ashrrev_i32_e32 v5, 31, v49
	v_or_b32_e32 v4, 0x80000000, v4
	v_or_b32_e32 v5, 0x80000000, v5
	v_xor_b32_e32 v48, v48, v4
	v_xor_b32_e32 v49, v49, v5
	v_cmp_ge_i32_e64 s[20:21], s17, v94
	v_cmp_ge_i32_e64 s[22:23], s18, v94
	s_nop 0
	v_cndmask_b32_e64 v48, 0, v48, s[20:21]
	v_cndmask_b32_e64 v49, 0, v49, s[22:23]
	s_sub_i32 s17, s8, 1152
	s_sub_i32 s18, s8, 1216
	v_add_f32_e32 v50, 0, v50
	v_add_f32_e32 v51, 0, v51
	v_ashrrev_i32_e32 v4, 31, v50
	v_ashrrev_i32_e32 v5, 31, v51
	v_or_b32_e32 v4, 0x80000000, v4
	v_or_b32_e32 v5, 0x80000000, v5
	v_xor_b32_e32 v50, v50, v4
	v_xor_b32_e32 v51, v51, v5
	v_cmp_ge_i32_e64 s[20:21], s17, v94
	v_cmp_ge_i32_e64 s[22:23], s18, v94
	s_nop 0
	v_cndmask_b32_e64 v50, 0, v50, s[20:21]
	v_cndmask_b32_e64 v51, 0, v51, s[22:23]
	s_sub_i32 s17, s8, 1280
	s_sub_i32 s18, s8, 1344
	v_add_f32_e32 v52, 0, v52
	v_add_f32_e32 v53, 0, v53
	v_ashrrev_i32_e32 v4, 31, v52
	v_ashrrev_i32_e32 v5, 31, v53
	v_or_b32_e32 v4, 0x80000000, v4
	v_or_b32_e32 v5, 0x80000000, v5
	v_xor_b32_e32 v52, v52, v4
	v_xor_b32_e32 v53, v53, v5
	v_cmp_ge_i32_e64 s[20:21], s17, v94
	v_cmp_ge_i32_e64 s[22:23], s18, v94
	s_nop 0
	v_cndmask_b32_e64 v52, 0, v52, s[20:21]
	v_cndmask_b32_e64 v53, 0, v53, s[22:23]
	s_sub_i32 s17, s8, 1408
	s_sub_i32 s18, s8, 1472
	v_add_f32_e32 v54, 0, v54
	v_add_f32_e32 v55, 0, v55
	v_ashrrev_i32_e32 v4, 31, v54
	v_ashrrev_i32_e32 v5, 31, v55
	v_or_b32_e32 v4, 0x80000000, v4
	v_or_b32_e32 v5, 0x80000000, v5
	v_xor_b32_e32 v54, v54, v4
	v_xor_b32_e32 v55, v55, v5
	v_cmp_ge_i32_e64 s[20:21], s17, v94
	v_cmp_ge_i32_e64 s[22:23], s18, v94
	s_nop 0
	v_cndmask_b32_e64 v54, 0, v54, s[20:21]
	v_cndmask_b32_e64 v55, 0, v55, s[22:23]
	s_cmp_lt_u32 s16, 3
	s_cbranch_scc1 .Lsel_loaded
	s_waitcnt lgkmcnt(0)
	s_sub_i32 s17, s8, 1536
	s_sub_i32 s18, s8, 1600
	v_add_f32_e32 v56, 0, v56
	v_add_f32_e32 v57, 0, v57
	v_ashrrev_i32_e32 v4, 31, v56
	v_ashrrev_i32_e32 v5, 31, v57
	v_or_b32_e32 v4, 0x80000000, v4
	v_or_b32_e32 v5, 0x80000000, v5
	v_xor_b32_e32 v56, v56, v4
	v_xor_b32_e32 v57, v57, v5
	v_cmp_ge_i32_e64 s[20:21], s17, v94
	v_cmp_ge_i32_e64 s[22:23], s18, v94
	s_nop 0
	v_cndmask_b32_e64 v56, 0, v56, s[20:21]
	v_cndmask_b32_e64 v57, 0, v57, s[22:23]
	s_sub_i32 s17, s8, 1664
	s_sub_i32 s18, s8, 1728
	v_add_f32_e32 v58, 0, v58
	v_add_f32_e32 v59, 0, v59
	v_ashrrev_i32_e32 v4, 31, v58
	v_ashrrev_i32_e32 v5, 31, v59
	v_or_b32_e32 v4, 0x80000000, v4
	v_or_b32_e32 v5, 0x80000000, v5
	v_xor_b32_e32 v58, v58, v4
	v_xor_b32_e32 v59, v59, v5
	v_cmp_ge_i32_e64 s[20:21], s17, v94
	v_cmp_ge_i32_e64 s[22:23], s18, v94
	s_nop 0
	v_cndmask_b32_e64 v58, 0, v58, s[20:21]
	v_cndmask_b32_e64 v59, 0, v59, s[22:23]
	s_sub_i32 s17, s8, 1792
	s_sub_i32 s18, s8, 1856
	v_add_f32_e32 v60, 0, v60
	v_add_f32_e32 v61, 0, v61
	v_ashrrev_i32_e32 v4, 31, v60
	v_ashrrev_i32_e32 v5, 31, v61
	v_or_b32_e32 v4, 0x80000000, v4
	v_or_b32_e32 v5, 0x80000000, v5
	v_xor_b32_e32 v60, v60, v4
	v_xor_b32_e32 v61, v61, v5
	v_cmp_ge_i32_e64 s[20:21], s17, v94
	v_cmp_ge_i32_e64 s[22:23], s18, v94
	s_nop 0
	v_cndmask_b32_e64 v60, 0, v60, s[20:21]
	v_cndmask_b32_e64 v61, 0, v61, s[22:23]
	s_sub_i32 s17, s8, 1920
	s_sub_i32 s18, s8, 1984
	v_add_f32_e32 v62, 0, v62
	v_add_f32_e32 v63, 0, v63
	v_ashrrev_i32_e32 v4, 31, v62
	v_ashrrev_i32_e32 v5, 31, v63
	v_or_b32_e32 v4, 0x80000000, v4
	v_or_b32_e32 v5, 0x80000000, v5
	v_xor_b32_e32 v62, v62, v4
	v_xor_b32_e32 v63, v63, v5
	v_cmp_ge_i32_e64 s[20:21], s17, v94
	v_cmp_ge_i32_e64 s[22:23], s18, v94
	s_nop 0
	v_cndmask_b32_e64 v62, 0, v62, s[20:21]
	v_cndmask_b32_e64 v63, 0, v63, s[22:23]
.Lsel_loaded:
	s_mov_b32 s10, 0
	s_brev_b32 s11, 1
.Lsel_bit:
	s_or_b32 s12, s10, s11
	v_mov_b32_e32 v1, 0
	v_cmp_ge_u32_e64 s[20:21], v32, s12
	v_cmp_ge_u32_e64 s[22:23], v33, s12
	v_cmp_ge_u32_e64 s[24:25], v34, s12
	v_cmp_ge_u32_e64 s[26:27], v35, s12
	v_addc_co_u32_e64 v1, vcc, 0, v1, s[20:21]
	v_cmp_ge_u32_e64 s[20:21], v36, s12
	v_addc_co_u32_e64 v1, vcc, 0, v1, s[22:23]
	v_cmp_ge_u32_e64 s[22:23], v37, s12
	v_addc_co_u32_e64 v1, vcc, 0, v1, s[24:25]
	v_cmp_ge_u32_e64 s[24:25], v38, s12
	v_addc_co_u32_e64 v1, vcc, 0, v1, s[26:27]
	v_cmp_ge_u32_e64 s[26:27], v39, s12
	v_addc_co_u32_e64 v1, vcc, 0, v1, s[20:21]
	v_addc_co_u32_e64 v1, vcc, 0, v1, s[22:23]
	v_addc_co_u32_e64 v1, vcc, 0, v1, s[24:25]
	v_addc_co_u32_e64 v1, vcc, 0, v1, s[26:27]
	s_cmp_lt_u32 s16, 1
	s_cbranch_scc1 .Lsel_red
	v_cmp_ge_u32_e64 s[20:21], v40, s12
	v_cmp_ge_u32_e64 s[22:23], v41, s12
	v_cmp_ge_u32_e64 s[24:25], v42, s12
	v_cmp_ge_u32_e64 s[26:27], v43, s12
	v_addc_co_u32_e64 v1, vcc, 0, v1, s[20:21]
	v_cmp_ge_u32_e64 s[20:21], v44, s12
	v_addc_co_u32_e64 v1, vcc, 0, v1, s[22:23]
	v_cmp_ge_u32_e64 s[22:23], v45, s12
	v_addc_co_u32_e64 v1, vcc, 0, v1, s[24:25]
	v_cmp_ge_u32_e64 s[24:25], v46, s12
	v_addc_co_u32_e64 v1, vcc, 0, v1, s[26:27]
	v_cmp_ge_u32_e64 s[26:27], v47, s12
	v_addc_co_u32_e64 v1, vcc, 0, v1, s[20:21]
	v_addc_co_u32_e64 v1, vcc, 0, v1, s[22:23]
	v_addc_co_u32_e64 v1, vcc, 0, v1, s[24:25]
	v_addc_co_u32_e64 v1, vcc, 0, v1, s[26:27]
	s_cmp_lt_u32 s16, 2
	s_cbranch_scc1 .Lsel_red
	v_cmp_ge_u32_e64 s[20:21], v48, s12
	v_cmp_ge_u32_e64 s[22:23], v49, s12
	v_cmp_ge_u32_e64 s[24:25], v50, s12
	v_cmp_ge_u32_e64 s[26:27], v51, s12
	v_addc_co_u32_e64 v1, vcc, 0, v1, s[20:21]
	v_cmp_ge_u32_e64 s[20:21], v52, s12
	v_addc_co_u32_e64 v1, vcc, 0, v1, s[22:23]
	v_cmp_ge_u32_e64 s[22:23], v53, s12
	v_addc_co_u32_e64 v1, vcc, 0, v1, s[24:25]
	v_cmp_ge_u32_e64 s[24:25], v54, s12
	v_addc_co_u32_e64 v1, vcc, 0, v1, s[26:27]
	v_cmp_ge_u32_e64 s[26:27], v55, s12
	v_addc_co_u32_e64 v1, vcc, 0, v1, s[20:21]
	v_addc_co_u32_e64 v1, vcc, 0, v1, s[22:23]
	v_addc_co_u32_e64 v1, vcc, 0, v1, s[24:25]
	v_addc_co_u32_e64 v1, vcc, 0, v1, s[26:27]
	s_cmp_lt_u32 s16, 3
	s_cbranch_scc1 .Lsel_red
	v_cmp_ge_u32_e64 s[20:21], v56, s12
	v_cmp_ge_u32_e64 s[22:23], v57, s12
	v_cmp_ge_u32_e64 s[24:25], v58, s12
	v_cmp_ge_u32_e64 s[26:27], v59, s12
	v_addc_co_u32_e64 v1, vcc, 0, v1, s[20:21]
	v_cmp_ge_u32_e64 s[20:21], v60, s12
	v_addc_co_u32_e64 v1, vcc, 0, v1, s[22:23]
	v_cmp_ge_u32_e64 s[22:23], v61, s12
	v_addc_co_u32_e64 v1, vcc, 0, v1, s[24:25]
	v_cmp_ge_u32_e64 s[24:25], v62, s12
	v_addc_co_u32_e64 v1, vcc, 0, v1, s[26:27]
	v_cmp_ge_u32_e64 s[26:27], v63, s12
	v_addc_co_u32_e64 v1, vcc, 0, v1, s[20:21]
	v_addc_co_u32_e64 v1, vcc, 0, v1, s[22:23]
	v_addc_co_u32_e64 v1, vcc, 0, v1, s[24:25]
	v_addc_co_u32_e64 v1, vcc, 0, v1, s[26:27]
.Lsel_red:
	s_nop 1
	v_add_u32_dpp v1, v1, v1 quad_perm:[1,0,3,2] row_mask:0xf bank_mask:0xf bound_ctrl:1
	s_nop 1
	v_add_u32_dpp v1, v1, v1 quad_perm:[2,3,0,1] row_mask:0xf bank_mask:0xf bound_ctrl:1
	s_nop 1
	v_add_u32_dpp v1, v1, v1 row_half_mirror row_mask:0xf bank_mask:0xf bound_ctrl:1
	s_nop 1
	v_add_u32_dpp v1, v1, v1 row_mirror row_mask:0xf bank_mask:0xf bound_ctrl:1
	s_nop 1
	v_readlane_b32 s13, v1, 0
	v_readlane_b32 s14, v1, 16
	v_readlane_b32 s15, v1, 32
	v_readlane_b32 s17, v1, 48
	s_add_i32 s13, s13, s14
	s_add_i32 s15, s15, s17
	s_add_i32 s13, s13, s15
	s_cmpk_lt_u32 s13, 0x100
	s_cselect_b32 s10, s10, s12
	s_cmpk_eq_i32 s13, 0x100
	s_cbranch_scc1 .Lsel_exact
	s_lshr_b32 s11, s11, 1
	s_cmp_lg_u32 s11, 0
	s_cbranch_scc1 .Lsel_bit
	s_mov_b32 s41, 0
	v_cmp_gt_u32_e64 s[20:21], v32, s10
	s_bcnt1_i32_b64 s14, s[20:21]
	s_add_i32 s41, s41, s14
	v_cmp_gt_u32_e64 s[20:21], v33, s10
	s_bcnt1_i32_b64 s14, s[20:21]
	s_add_i32 s41, s41, s14
	v_cmp_gt_u32_e64 s[20:21], v34, s10
	s_bcnt1_i32_b64 s14, s[20:21]
	s_add_i32 s41, s41, s14
	v_cmp_gt_u32_e64 s[20:21], v35, s10
	s_bcnt1_i32_b64 s14, s[20:21]
	s_add_i32 s41, s41, s14
	v_cmp_gt_u32_e64 s[20:21], v36, s10
	s_bcnt1_i32_b64 s14, s[20:21]
	s_add_i32 s41, s41, s14
	v_cmp_gt_u32_e64 s[20:21], v37, s10
	s_bcnt1_i32_b64 s14, s[20:21]
	s_add_i32 s41, s41, s14
	v_cmp_gt_u32_e64 s[20:21], v38, s10
	s_bcnt1_i32_b64 s14, s[20:21]
	s_add_i32 s41, s41, s14
	v_cmp_gt_u32_e64 s[20:21], v39, s10
	s_bcnt1_i32_b64 s14, s[20:21]
	s_add_i32 s41, s41, s14
	s_cmp_lt_u32 s16, 1
	s_cbranch_scc1 .Lsel_gdone
	v_cmp_gt_u32_e64 s[20:21], v40, s10
	s_bcnt1_i32_b64 s14, s[20:21]
	s_add_i32 s41, s41, s14
	v_cmp_gt_u32_e64 s[20:21], v41, s10
	s_bcnt1_i32_b64 s14, s[20:21]
	s_add_i32 s41, s41, s14
	v_cmp_gt_u32_e64 s[20:21], v42, s10
	s_bcnt1_i32_b64 s14, s[20:21]
	s_add_i32 s41, s41, s14
	v_cmp_gt_u32_e64 s[20:21], v43, s10
	s_bcnt1_i32_b64 s14, s[20:21]
	s_add_i32 s41, s41, s14
	v_cmp_gt_u32_e64 s[20:21], v44, s10
	s_bcnt1_i32_b64 s14, s[20:21]
	s_add_i32 s41, s41, s14
	v_cmp_gt_u32_e64 s[20:21], v45, s10
	s_bcnt1_i32_b64 s14, s[20:21]
	s_add_i32 s41, s41, s14
	v_cmp_gt_u32_e64 s[20:21], v46, s10
	s_bcnt1_i32_b64 s14, s[20:21]
	s_add_i32 s41, s41, s14
	v_cmp_gt_u32_e64 s[20:21], v47, s10
	s_bcnt1_i32_b64 s14, s[20:21]
	s_add_i32 s41, s41, s14
	s_cmp_lt_u32 s16, 2
	s_cbranch_scc1 .Lsel_gdone
	v_cmp_gt_u32_e64 s[20:21], v48, s10
	s_bcnt1_i32_b64 s14, s[20:21]
	s_add_i32 s41, s41, s14
	v_cmp_gt_u32_e64 s[20:21], v49, s10
	s_bcnt1_i32_b64 s14, s[20:21]
	s_add_i32 s41, s41, s14
	v_cmp_gt_u32_e64 s[20:21], v50, s10
	s_bcnt1_i32_b64 s14, s[20:21]
	s_add_i32 s41, s41, s14
	v_cmp_gt_u32_e64 s[20:21], v51, s10
	s_bcnt1_i32_b64 s14, s[20:21]
	s_add_i32 s41, s41, s14
	v_cmp_gt_u32_e64 s[20:21], v52, s10
	s_bcnt1_i32_b64 s14, s[20:21]
	s_add_i32 s41, s41, s14
	v_cmp_gt_u32_e64 s[20:21], v53, s10
	s_bcnt1_i32_b64 s14, s[20:21]
	s_add_i32 s41, s41, s14
	v_cmp_gt_u32_e64 s[20:21], v54, s10
	s_bcnt1_i32_b64 s14, s[20:21]
	s_add_i32 s41, s41, s14
	v_cmp_gt_u32_e64 s[20:21], v55, s10
	s_bcnt1_i32_b64 s14, s[20:21]
	s_add_i32 s41, s41, s14
	s_cmp_lt_u32 s16, 3
	s_cbranch_scc1 .Lsel_gdone
	v_cmp_gt_u32_e64 s[20:21], v56, s10
	s_bcnt1_i32_b64 s14, s[20:21]
	s_add_i32 s41, s41, s14
	v_cmp_gt_u32_e64 s[20:21], v57, s10
	s_bcnt1_i32_b64 s14, s[20:21]
	s_add_i32 s41, s41, s14
	v_cmp_gt_u32_e64 s[20:21], v58, s10
	s_bcnt1_i32_b64 s14, s[20:21]
	s_add_i32 s41, s41, s14
	v_cmp_gt_u32_e64 s[20:21], v59, s10
	s_bcnt1_i32_b64 s14, s[20:21]
	s_add_i32 s41, s41, s14
	v_cmp_gt_u32_e64 s[20:21], v60, s10
	s_bcnt1_i32_b64 s14, s[20:21]
	s_add_i32 s41, s41, s14
	v_cmp_gt_u32_e64 s[20:21], v61, s10
	s_bcnt1_i32_b64 s14, s[20:21]
	s_add_i32 s41, s41, s14
	v_cmp_gt_u32_e64 s[20:21], v62, s10
	s_bcnt1_i32_b64 s14, s[20:21]
	s_add_i32 s41, s41, s14
	v_cmp_gt_u32_e64 s[20:21], v63, s10
	s_bcnt1_i32_b64 s14, s[20:21]
	s_add_i32 s41, s41, s14
.Lsel_gdone:
	s_sub_i32 s39, 0x100, s41
	s_mov_b32 s40, 0
	v_mov_b32_e32 v2, 0
	v_mov_b32_e32 v3, 0
	v_cmp_gt_u32_e64 s[20:21], v32, s10
	v_cmp_eq_u32_e64 s[22:23], v32, s10
	s_nop 1
	v_mbcnt_lo_u32_b32 v4, s22, 0
	v_mbcnt_hi_u32_b32 v4, s23, v4
	v_add_u32_e32 v4, s40, v4
	v_cmp_gt_u32_e64 s[24:25], s39, v4
	s_bcnt1_i32_b64 s14, s[22:23]
	s_add_i32 s40, s40, s14
	s_and_b64 s[24:25], s[24:25], s[22:23]
	s_or_b64 s[20:21], s[20:21], s[24:25]
	s_nop 0
	v_writelane_b32 v2, s20, 0
	v_writelane_b32 v3, s21, 0
	v_cmp_gt_u32_e64 s[20:21], v33, s10
	v_cmp_eq_u32_e64 s[22:23], v33, s10
	s_nop 1
	v_mbcnt_lo_u32_b32 v4, s22, 0
	v_mbcnt_hi_u32_b32 v4, s23, v4
	v_add_u32_e32 v4, s40, v4
	v_cmp_gt_u32_e64 s[24:25], s39, v4
	s_bcnt1_i32_b64 s14, s[22:23]
	s_add_i32 s40, s40, s14
	s_and_b64 s[24:25], s[24:25], s[22:23]
	s_or_b64 s[20:21], s[20:21], s[24:25]
	s_nop 0
	v_writelane_b32 v2, s20, 1
	v_writelane_b32 v3, s21, 1
	v_cmp_gt_u32_e64 s[20:21], v34, s10
	v_cmp_eq_u32_e64 s[22:23], v34, s10
	s_nop 1
	v_mbcnt_lo_u32_b32 v4, s22, 0
	v_mbcnt_hi_u32_b32 v4, s23, v4
	v_add_u32_e32 v4, s40, v4
	v_cmp_gt_u32_e64 s[24:25], s39, v4
	s_bcnt1_i32_b64 s14, s[22:23]
	s_add_i32 s40, s40, s14
	s_and_b64 s[24:25], s[24:25], s[22:23]
	s_or_b64 s[20:21], s[20:21], s[24:25]
	s_nop 0
	v_writelane_b32 v2, s20, 2
	v_writelane_b32 v3, s21, 2
	v_cmp_gt_u32_e64 s[20:21], v35, s10
	v_cmp_eq_u32_e64 s[22:23], v35, s10
	s_nop 1
	v_mbcnt_lo_u32_b32 v4, s22, 0
	v_mbcnt_hi_u32_b32 v4, s23, v4
	v_add_u32_e32 v4, s40, v4
	v_cmp_gt_u32_e64 s[24:25], s39, v4
	s_bcnt1_i32_b64 s14, s[22:23]
	s_add_i32 s40, s40, s14
	s_and_b64 s[24:25], s[24:25], s[22:23]
	s_or_b64 s[20:21], s[20:21], s[24:25]
	s_nop 0
	v_writelane_b32 v2, s20, 3
	v_writelane_b32 v3, s21, 3
	v_cmp_gt_u32_e64 s[20:21], v36, s10
	v_cmp_eq_u32_e64 s[22:23], v36, s10
	s_nop 1
	v_mbcnt_lo_u32_b32 v4, s22, 0
	v_mbcnt_hi_u32_b32 v4, s23, v4
	v_add_u32_e32 v4, s40, v4
	v_cmp_gt_u32_e64 s[24:25], s39, v4
	s_bcnt1_i32_b64 s14, s[22:23]
	s_add_i32 s40, s40, s14
	s_and_b64 s[24:25], s[24:25], s[22:23]
	s_or_b64 s[20:21], s[20:21], s[24:25]
	s_nop 0
	v_writelane_b32 v2, s20, 4
	v_writelane_b32 v3, s21, 4
	v_cmp_gt_u32_e64 s[20:21], v37, s10
	v_cmp_eq_u32_e64 s[22:23], v37, s10
	s_nop 1
	v_mbcnt_lo_u32_b32 v4, s22, 0
	v_mbcnt_hi_u32_b32 v4, s23, v4
	v_add_u32_e32 v4, s40, v4
	v_cmp_gt_u32_e64 s[24:25], s39, v4
	s_bcnt1_i32_b64 s14, s[22:23]
	s_add_i32 s40, s40, s14
	s_and_b64 s[24:25], s[24:25], s[22:23]
	s_or_b64 s[20:21], s[20:21], s[24:25]
	s_nop 0
	v_writelane_b32 v2, s20, 5
	v_writelane_b32 v3, s21, 5
	v_cmp_gt_u32_e64 s[20:21], v38, s10
	v_cmp_eq_u32_e64 s[22:23], v38, s10
	s_nop 1
	v_mbcnt_lo_u32_b32 v4, s22, 0
	v_mbcnt_hi_u32_b32 v4, s23, v4
	v_add_u32_e32 v4, s40, v4
	v_cmp_gt_u32_e64 s[24:25], s39, v4
	s_bcnt1_i32_b64 s14, s[22:23]
	s_add_i32 s40, s40, s14
	s_and_b64 s[24:25], s[24:25], s[22:23]
	s_or_b64 s[20:21], s[20:21], s[24:25]
	s_nop 0
	v_writelane_b32 v2, s20, 6
	v_writelane_b32 v3, s21, 6
	v_cmp_gt_u32_e64 s[20:21], v39, s10
	v_cmp_eq_u32_e64 s[22:23], v39, s10
	s_nop 1
	v_mbcnt_lo_u32_b32 v4, s22, 0
	v_mbcnt_hi_u32_b32 v4, s23, v4
	v_add_u32_e32 v4, s40, v4
	v_cmp_gt_u32_e64 s[24:25], s39, v4
	s_bcnt1_i32_b64 s14, s[22:23]
	s_add_i32 s40, s40, s14
	s_and_b64 s[24:25], s[24:25], s[22:23]
	s_or_b64 s[20:21], s[20:21], s[24:25]
	s_nop 0
	v_writelane_b32 v2, s20, 7
	v_writelane_b32 v3, s21, 7
	s_cmp_lt_u32 s16, 1
	s_cbranch_scc1 .Lsel_store
	v_cmp_gt_u32_e64 s[20:21], v40, s10
	v_cmp_eq_u32_e64 s[22:23], v40, s10
	s_nop 1
	v_mbcnt_lo_u32_b32 v4, s22, 0
	v_mbcnt_hi_u32_b32 v4, s23, v4
	v_add_u32_e32 v4, s40, v4
	v_cmp_gt_u32_e64 s[24:25], s39, v4
	s_bcnt1_i32_b64 s14, s[22:23]
	s_add_i32 s40, s40, s14
	s_and_b64 s[24:25], s[24:25], s[22:23]
	s_or_b64 s[20:21], s[20:21], s[24:25]
	s_nop 0
	v_writelane_b32 v2, s20, 8
	v_writelane_b32 v3, s21, 8
	v_cmp_gt_u32_e64 s[20:21], v41, s10
	v_cmp_eq_u32_e64 s[22:23], v41, s10
	s_nop 1
	v_mbcnt_lo_u32_b32 v4, s22, 0
	v_mbcnt_hi_u32_b32 v4, s23, v4
	v_add_u32_e32 v4, s40, v4
	v_cmp_gt_u32_e64 s[24:25], s39, v4
	s_bcnt1_i32_b64 s14, s[22:23]
	s_add_i32 s40, s40, s14
	s_and_b64 s[24:25], s[24:25], s[22:23]
	s_or_b64 s[20:21], s[20:21], s[24:25]
	s_nop 0
	v_writelane_b32 v2, s20, 9
	v_writelane_b32 v3, s21, 9
	v_cmp_gt_u32_e64 s[20:21], v42, s10
	v_cmp_eq_u32_e64 s[22:23], v42, s10
	s_nop 1
	v_mbcnt_lo_u32_b32 v4, s22, 0
	v_mbcnt_hi_u32_b32 v4, s23, v4
	v_add_u32_e32 v4, s40, v4
	v_cmp_gt_u32_e64 s[24:25], s39, v4
	s_bcnt1_i32_b64 s14, s[22:23]
	s_add_i32 s40, s40, s14
	s_and_b64 s[24:25], s[24:25], s[22:23]
	s_or_b64 s[20:21], s[20:21], s[24:25]
	s_nop 0
	v_writelane_b32 v2, s20, 10
	v_writelane_b32 v3, s21, 10
	v_cmp_gt_u32_e64 s[20:21], v43, s10
	v_cmp_eq_u32_e64 s[22:23], v43, s10
	s_nop 1
	v_mbcnt_lo_u32_b32 v4, s22, 0
	v_mbcnt_hi_u32_b32 v4, s23, v4
	v_add_u32_e32 v4, s40, v4
	v_cmp_gt_u32_e64 s[24:25], s39, v4
	s_bcnt1_i32_b64 s14, s[22:23]
	s_add_i32 s40, s40, s14
	s_and_b64 s[24:25], s[24:25], s[22:23]
	s_or_b64 s[20:21], s[20:21], s[24:25]
	s_nop 0
	v_writelane_b32 v2, s20, 11
	v_writelane_b32 v3, s21, 11
	v_cmp_gt_u32_e64 s[20:21], v44, s10
	v_cmp_eq_u32_e64 s[22:23], v44, s10
	s_nop 1
	v_mbcnt_lo_u32_b32 v4, s22, 0
	v_mbcnt_hi_u32_b32 v4, s23, v4
	v_add_u32_e32 v4, s40, v4
	v_cmp_gt_u32_e64 s[24:25], s39, v4
	s_bcnt1_i32_b64 s14, s[22:23]
	s_add_i32 s40, s40, s14
	s_and_b64 s[24:25], s[24:25], s[22:23]
	s_or_b64 s[20:21], s[20:21], s[24:25]
	s_nop 0
	v_writelane_b32 v2, s20, 12
	v_writelane_b32 v3, s21, 12
	v_cmp_gt_u32_e64 s[20:21], v45, s10
	v_cmp_eq_u32_e64 s[22:23], v45, s10
	s_nop 1
	v_mbcnt_lo_u32_b32 v4, s22, 0
	v_mbcnt_hi_u32_b32 v4, s23, v4
	v_add_u32_e32 v4, s40, v4
	v_cmp_gt_u32_e64 s[24:25], s39, v4
	s_bcnt1_i32_b64 s14, s[22:23]
	s_add_i32 s40, s40, s14
	s_and_b64 s[24:25], s[24:25], s[22:23]
	s_or_b64 s[20:21], s[20:21], s[24:25]
	s_nop 0
	v_writelane_b32 v2, s20, 13
	v_writelane_b32 v3, s21, 13
	v_cmp_gt_u32_e64 s[20:21], v46, s10
	v_cmp_eq_u32_e64 s[22:23], v46, s10
	s_nop 1
	v_mbcnt_lo_u32_b32 v4, s22, 0
	v_mbcnt_hi_u32_b32 v4, s23, v4
	v_add_u32_e32 v4, s40, v4
	v_cmp_gt_u32_e64 s[24:25], s39, v4
	s_bcnt1_i32_b64 s14, s[22:23]
	s_add_i32 s40, s40, s14
	s_and_b64 s[24:25], s[24:25], s[22:23]
	s_or_b64 s[20:21], s[20:21], s[24:25]
	s_nop 0
	v_writelane_b32 v2, s20, 14
	v_writelane_b32 v3, s21, 14
	v_cmp_gt_u32_e64 s[20:21], v47, s10
	v_cmp_eq_u32_e64 s[22:23], v47, s10
	s_nop 1
	v_mbcnt_lo_u32_b32 v4, s22, 0
	v_mbcnt_hi_u32_b32 v4, s23, v4
	v_add_u32_e32 v4, s40, v4
	v_cmp_gt_u32_e64 s[24:25], s39, v4
	s_bcnt1_i32_b64 s14, s[22:23]
	s_add_i32 s40, s40, s14
	s_and_b64 s[24:25], s[24:25], s[22:23]
	s_or_b64 s[20:21], s[20:21], s[24:25]
	s_nop 0
	v_writelane_b32 v2, s20, 15
	v_writelane_b32 v3, s21, 15
	s_cmp_lt_u32 s16, 2
	s_cbranch_scc1 .Lsel_store
	v_cmp_gt_u32_e64 s[20:21], v48, s10
	v_cmp_eq_u32_e64 s[22:23], v48, s10
	s_nop 1
	v_mbcnt_lo_u32_b32 v4, s22, 0
	v_mbcnt_hi_u32_b32 v4, s23, v4
	v_add_u32_e32 v4, s40, v4
	v_cmp_gt_u32_e64 s[24:25], s39, v4
	s_bcnt1_i32_b64 s14, s[22:23]
	s_add_i32 s40, s40, s14
	s_and_b64 s[24:25], s[24:25], s[22:23]
	s_or_b64 s[20:21], s[20:21], s[24:25]
	s_nop 0
	v_writelane_b32 v2, s20, 16
	v_writelane_b32 v3, s21, 16
	v_cmp_gt_u32_e64 s[20:21], v49, s10
	v_cmp_eq_u32_e64 s[22:23], v49, s10
	s_nop 1
	v_mbcnt_lo_u32_b32 v4, s22, 0
	v_mbcnt_hi_u32_b32 v4, s23, v4
	v_add_u32_e32 v4, s40, v4
	v_cmp_gt_u32_e64 s[24:25], s39, v4
	s_bcnt1_i32_b64 s14, s[22:23]
	s_add_i32 s40, s40, s14
	s_and_b64 s[24:25], s[24:25], s[22:23]
	s_or_b64 s[20:21], s[20:21], s[24:25]
	s_nop 0
	v_writelane_b32 v2, s20, 17
	v_writelane_b32 v3, s21, 17
	v_cmp_gt_u32_e64 s[20:21], v50, s10
	v_cmp_eq_u32_e64 s[22:23], v50, s10
	s_nop 1
	v_mbcnt_lo_u32_b32 v4, s22, 0
	v_mbcnt_hi_u32_b32 v4, s23, v4
	v_add_u32_e32 v4, s40, v4
	v_cmp_gt_u32_e64 s[24:25], s39, v4
	s_bcnt1_i32_b64 s14, s[22:23]
	s_add_i32 s40, s40, s14
	s_and_b64 s[24:25], s[24:25], s[22:23]
	s_or_b64 s[20:21], s[20:21], s[24:25]
	s_nop 0
	v_writelane_b32 v2, s20, 18
	v_writelane_b32 v3, s21, 18
	v_cmp_gt_u32_e64 s[20:21], v51, s10
	v_cmp_eq_u32_e64 s[22:23], v51, s10
	s_nop 1
	v_mbcnt_lo_u32_b32 v4, s22, 0
	v_mbcnt_hi_u32_b32 v4, s23, v4
	v_add_u32_e32 v4, s40, v4
	v_cmp_gt_u32_e64 s[24:25], s39, v4
	s_bcnt1_i32_b64 s14, s[22:23]
	s_add_i32 s40, s40, s14
	s_and_b64 s[24:25], s[24:25], s[22:23]
	s_or_b64 s[20:21], s[20:21], s[24:25]
	s_nop 0
	v_writelane_b32 v2, s20, 19
	v_writelane_b32 v3, s21, 19
	v_cmp_gt_u32_e64 s[20:21], v52, s10
	v_cmp_eq_u32_e64 s[22:23], v52, s10
	s_nop 1
	v_mbcnt_lo_u32_b32 v4, s22, 0
	v_mbcnt_hi_u32_b32 v4, s23, v4
	v_add_u32_e32 v4, s40, v4
	v_cmp_gt_u32_e64 s[24:25], s39, v4
	s_bcnt1_i32_b64 s14, s[22:23]
	s_add_i32 s40, s40, s14
	s_and_b64 s[24:25], s[24:25], s[22:23]
	s_or_b64 s[20:21], s[20:21], s[24:25]
	s_nop 0
	v_writelane_b32 v2, s20, 20
	v_writelane_b32 v3, s21, 20
	v_cmp_gt_u32_e64 s[20:21], v53, s10
	v_cmp_eq_u32_e64 s[22:23], v53, s10
	s_nop 1
	v_mbcnt_lo_u32_b32 v4, s22, 0
	v_mbcnt_hi_u32_b32 v4, s23, v4
	v_add_u32_e32 v4, s40, v4
	v_cmp_gt_u32_e64 s[24:25], s39, v4
	s_bcnt1_i32_b64 s14, s[22:23]
	s_add_i32 s40, s40, s14
	s_and_b64 s[24:25], s[24:25], s[22:23]
	s_or_b64 s[20:21], s[20:21], s[24:25]
	s_nop 0
	v_writelane_b32 v2, s20, 21
	v_writelane_b32 v3, s21, 21
	v_cmp_gt_u32_e64 s[20:21], v54, s10
	v_cmp_eq_u32_e64 s[22:23], v54, s10
	s_nop 1
	v_mbcnt_lo_u32_b32 v4, s22, 0
	v_mbcnt_hi_u32_b32 v4, s23, v4
	v_add_u32_e32 v4, s40, v4
	v_cmp_gt_u32_e64 s[24:25], s39, v4
	s_bcnt1_i32_b64 s14, s[22:23]
	s_add_i32 s40, s40, s14
	s_and_b64 s[24:25], s[24:25], s[22:23]
	s_or_b64 s[20:21], s[20:21], s[24:25]
	s_nop 0
	v_writelane_b32 v2, s20, 22
	v_writelane_b32 v3, s21, 22
	v_cmp_gt_u32_e64 s[20:21], v55, s10
	v_cmp_eq_u32_e64 s[22:23], v55, s10
	s_nop 1
	v_mbcnt_lo_u32_b32 v4, s22, 0
	v_mbcnt_hi_u32_b32 v4, s23, v4
	v_add_u32_e32 v4, s40, v4
	v_cmp_gt_u32_e64 s[24:25], s39, v4
	s_bcnt1_i32_b64 s14, s[22:23]
	s_add_i32 s40, s40, s14
	s_and_b64 s[24:25], s[24:25], s[22:23]
	s_or_b64 s[20:21], s[20:21], s[24:25]
	s_nop 0
	v_writelane_b32 v2, s20, 23
	v_writelane_b32 v3, s21, 23
	s_cmp_lt_u32 s16, 3
	s_cbranch_scc1 .Lsel_store
	v_cmp_gt_u32_e64 s[20:21], v56, s10
	v_cmp_eq_u32_e64 s[22:23], v56, s10
	s_nop 1
	v_mbcnt_lo_u32_b32 v4, s22, 0
	v_mbcnt_hi_u32_b32 v4, s23, v4
	v_add_u32_e32 v4, s40, v4
	v_cmp_gt_u32_e64 s[24:25], s39, v4
	s_bcnt1_i32_b64 s14, s[22:23]
	s_add_i32 s40, s40, s14
	s_and_b64 s[24:25], s[24:25], s[22:23]
	s_or_b64 s[20:21], s[20:21], s[24:25]
	s_nop 0
	v_writelane_b32 v2, s20, 24
	v_writelane_b32 v3, s21, 24
	v_cmp_gt_u32_e64 s[20:21], v57, s10
	v_cmp_eq_u32_e64 s[22:23], v57, s10
	s_nop 1
	v_mbcnt_lo_u32_b32 v4, s22, 0
	v_mbcnt_hi_u32_b32 v4, s23, v4
	v_add_u32_e32 v4, s40, v4
	v_cmp_gt_u32_e64 s[24:25], s39, v4
	s_bcnt1_i32_b64 s14, s[22:23]
	s_add_i32 s40, s40, s14
	s_and_b64 s[24:25], s[24:25], s[22:23]
	s_or_b64 s[20:21], s[20:21], s[24:25]
	s_nop 0
	v_writelane_b32 v2, s20, 25
	v_writelane_b32 v3, s21, 25
	v_cmp_gt_u32_e64 s[20:21], v58, s10
	v_cmp_eq_u32_e64 s[22:23], v58, s10
	s_nop 1
	v_mbcnt_lo_u32_b32 v4, s22, 0
	v_mbcnt_hi_u32_b32 v4, s23, v4
	v_add_u32_e32 v4, s40, v4
	v_cmp_gt_u32_e64 s[24:25], s39, v4
	s_bcnt1_i32_b64 s14, s[22:23]
	s_add_i32 s40, s40, s14
	s_and_b64 s[24:25], s[24:25], s[22:23]
	s_or_b64 s[20:21], s[20:21], s[24:25]
	s_nop 0
	v_writelane_b32 v2, s20, 26
	v_writelane_b32 v3, s21, 26
	v_cmp_gt_u32_e64 s[20:21], v59, s10
	v_cmp_eq_u32_e64 s[22:23], v59, s10
	s_nop 1
	v_mbcnt_lo_u32_b32 v4, s22, 0
	v_mbcnt_hi_u32_b32 v4, s23, v4
	v_add_u32_e32 v4, s40, v4
	v_cmp_gt_u32_e64 s[24:25], s39, v4
	s_bcnt1_i32_b64 s14, s[22:23]
	s_add_i32 s40, s40, s14
	s_and_b64 s[24:25], s[24:25], s[22:23]
	s_or_b64 s[20:21], s[20:21], s[24:25]
	s_nop 0
	v_writelane_b32 v2, s20, 27
	v_writelane_b32 v3, s21, 27
	v_cmp_gt_u32_e64 s[20:21], v60, s10
	v_cmp_eq_u32_e64 s[22:23], v60, s10
	s_nop 1
	v_mbcnt_lo_u32_b32 v4, s22, 0
	v_mbcnt_hi_u32_b32 v4, s23, v4
	v_add_u32_e32 v4, s40, v4
	v_cmp_gt_u32_e64 s[24:25], s39, v4
	s_bcnt1_i32_b64 s14, s[22:23]
	s_add_i32 s40, s40, s14
	s_and_b64 s[24:25], s[24:25], s[22:23]
	s_or_b64 s[20:21], s[20:21], s[24:25]
	s_nop 0
	v_writelane_b32 v2, s20, 28
	v_writelane_b32 v3, s21, 28
	v_cmp_gt_u32_e64 s[20:21], v61, s10
	v_cmp_eq_u32_e64 s[22:23], v61, s10
	s_nop 1
	v_mbcnt_lo_u32_b32 v4, s22, 0
	v_mbcnt_hi_u32_b32 v4, s23, v4
	v_add_u32_e32 v4, s40, v4
	v_cmp_gt_u32_e64 s[24:25], s39, v4
	s_bcnt1_i32_b64 s14, s[22:23]
	s_add_i32 s40, s40, s14
	s_and_b64 s[24:25], s[24:25], s[22:23]
	s_or_b64 s[20:21], s[20:21], s[24:25]
	s_nop 0
	v_writelane_b32 v2, s20, 29
	v_writelane_b32 v3, s21, 29
	v_cmp_gt_u32_e64 s[20:21], v62, s10
	v_cmp_eq_u32_e64 s[22:23], v62, s10
	s_nop 1
	v_mbcnt_lo_u32_b32 v4, s22, 0
	v_mbcnt_hi_u32_b32 v4, s23, v4
	v_add_u32_e32 v4, s40, v4
	v_cmp_gt_u32_e64 s[24:25], s39, v4
	s_bcnt1_i32_b64 s14, s[22:23]
	s_add_i32 s40, s40, s14
	s_and_b64 s[24:25], s[24:25], s[22:23]
	s_or_b64 s[20:21], s[20:21], s[24:25]
	s_nop 0
	v_writelane_b32 v2, s20, 30
	v_writelane_b32 v3, s21, 30
	v_cmp_gt_u32_e64 s[20:21], v63, s10
	v_cmp_eq_u32_e64 s[22:23], v63, s10
	s_nop 1
	v_mbcnt_lo_u32_b32 v4, s22, 0
	v_mbcnt_hi_u32_b32 v4, s23, v4
	v_add_u32_e32 v4, s40, v4
	v_cmp_gt_u32_e64 s[24:25], s39, v4
	s_bcnt1_i32_b64 s14, s[22:23]
	s_add_i32 s40, s40, s14
	s_and_b64 s[24:25], s[24:25], s[22:23]
	s_or_b64 s[20:21], s[20:21], s[24:25]
	s_nop 0
	v_writelane_b32 v2, s20, 31
	v_writelane_b32 v3, s21, 31
	s_branch .Lsel_store
.Lsel_exact:
	v_mov_b32_e32 v2, 0
	v_mov_b32_e32 v3, 0
	v_cmp_ge_u32_e64 s[20:21], v32, s10
	v_cmp_ge_u32_e64 s[22:23], v33, s10
	v_cmp_ge_u32_e64 s[24:25], v34, s10
	v_cmp_ge_u32_e64 s[26:27], v35, s10
	v_writelane_b32 v2, s20, 0
	v_writelane_b32 v3, s21, 0
	v_cmp_ge_u32_e64 s[20:21], v36, s10
	v_writelane_b32 v2, s22, 1
	v_writelane_b32 v3, s23, 1
	v_cmp_ge_u32_e64 s[22:23], v37, s10
	v_writelane_b32 v2, s24, 2
	v_writelane_b32 v3, s25, 2
	v_cmp_ge_u32_e64 s[24:25], v38, s10
	v_writelane_b32 v2, s26, 3
	v_writelane_b32 v3, s27, 3
	v_cmp_ge_u32_e64 s[26:27], v39, s10
	v_writelane_b32 v2, s20, 4
	v_writelane_b32 v3, s21, 4
	v_writelane_b32 v2, s22, 5
	v_writelane_b32 v3, s23, 5
	v_writelane_b32 v2, s24, 6
	v_writelane_b32 v3, s25, 6
	v_writelane_b32 v2, s26, 7
	v_writelane_b32 v3, s27, 7
	s_cmp_lt_u32 s16, 1
	s_cbranch_scc1 .Lsel_store
	v_cmp_ge_u32_e64 s[20:21], v40, s10
	v_cmp_ge_u32_e64 s[22:23], v41, s10
	v_cmp_ge_u32_e64 s[24:25], v42, s10
	v_cmp_ge_u32_e64 s[26:27], v43, s10
	v_writelane_b32 v2, s20, 8
	v_writelane_b32 v3, s21, 8
	v_cmp_ge_u32_e64 s[20:21], v44, s10
	v_writelane_b32 v2, s22, 9
	v_writelane_b32 v3, s23, 9
	v_cmp_ge_u32_e64 s[22:23], v45, s10
	v_writelane_b32 v2, s24, 10
	v_writelane_b32 v3, s25, 10
	v_cmp_ge_u32_e64 s[24:25], v46, s10
	v_writelane_b32 v2, s26, 11
	v_writelane_b32 v3, s27, 11
	v_cmp_ge_u32_e64 s[26:27], v47, s10
	v_writelane_b32 v2, s20, 12
	v_writelane_b32 v3, s21, 12
	v_writelane_b32 v2, s22, 13
	v_writelane_b32 v3, s23, 13
	v_writelane_b32 v2, s24, 14
	v_writelane_b32 v3, s25, 14
	v_writelane_b32 v2, s26, 15
	v_writelane_b32 v3, s27, 15
	s_cmp_lt_u32 s16, 2
	s_cbranch_scc1 .Lsel_store
	v_cmp_ge_u32_e64 s[20:21], v48, s10
	v_cmp_ge_u32_e64 s[22:23], v49, s10
	v_cmp_ge_u32_e64 s[24:25], v50, s10
	v_cmp_ge_u32_e64 s[26:27], v51, s10
	v_writelane_b32 v2, s20, 16
	v_writelane_b32 v3, s21, 16
	v_cmp_ge_u32_e64 s[20:21], v52, s10
	v_writelane_b32 v2, s22, 17
	v_writelane_b32 v3, s23, 17
	v_cmp_ge_u32_e64 s[22:23], v53, s10
	v_writelane_b32 v2, s24, 18
	v_writelane_b32 v3, s25, 18
	v_cmp_ge_u32_e64 s[24:25], v54, s10
	v_writelane_b32 v2, s26, 19
	v_writelane_b32 v3, s27, 19
	v_cmp_ge_u32_e64 s[26:27], v55, s10
	v_writelane_b32 v2, s20, 20
	v_writelane_b32 v3, s21, 20
	v_writelane_b32 v2, s22, 21
	v_writelane_b32 v3, s23, 21
	v_writelane_b32 v2, s24, 22
	v_writelane_b32 v3, s25, 22
	v_writelane_b32 v2, s26, 23
	v_writelane_b32 v3, s27, 23
	s_cmp_lt_u32 s16, 3
	s_cbranch_scc1 .Lsel_store
	v_cmp_ge_u32_e64 s[20:21], v56, s10
	v_cmp_ge_u32_e64 s[22:23], v57, s10
	v_cmp_ge_u32_e64 s[24:25], v58, s10
	v_cmp_ge_u32_e64 s[26:27], v59, s10
	v_writelane_b32 v2, s20, 24
	v_writelane_b32 v3, s21, 24
	v_cmp_ge_u32_e64 s[20:21], v60, s10
	v_writelane_b32 v2, s22, 25
	v_writelane_b32 v3, s23, 25
	v_cmp_ge_u32_e64 s[22:23], v61, s10
	v_writelane_b32 v2, s24, 26
	v_writelane_b32 v3, s25, 26
	v_cmp_ge_u32_e64 s[24:25], v62, s10
	v_writelane_b32 v2, s26, 27
	v_writelane_b32 v3, s27, 27
	v_cmp_ge_u32_e64 s[26:27], v63, s10
	v_writelane_b32 v2, s20, 28
	v_writelane_b32 v3, s21, 28
	v_writelane_b32 v2, s22, 29
	v_writelane_b32 v3, s23, 29
	v_writelane_b32 v2, s24, 30
	v_writelane_b32 v3, s25, 30
	v_writelane_b32 v2, s26, 31
	v_writelane_b32 v3, s27, 31
.Lsel_store:
	v_readlane_b32 s0, v254, 39
	v_readlane_b32 s1, v254, 40
	v_readlane_b32 s4, v254, 41
	s_mov_b32 s5, 0
	s_add_i32 s4, s4, s8
	s_lshl_b64 s[4:5], s[4:5], 8
	s_add_u32 s0, s0, s4
	s_addc_u32 s1, s1, s5
	v_lshlrev_b32_e32 v4, 3, v94
	v_cmp_gt_u32_e32 vcc, 32, v94
	s_and_saveexec_b64 s[48:49], vcc
	global_store_dwordx2 v4, v[2:3], s[0:1]
	s_or_b64 exec, exec, s[48:49]
	s_add_i32 s38, s38, 1
	s_cmp_lt_u32 s38, 2
	s_cbranch_scc1 .Lsel_q
	v_readlane_b32 s0, v254, 44
	v_readlane_b32 s1, v254, 45
	v_mov_b64_e32 v[4:5], s[6:7]
	s_nop 0
	v_mov_b64_e32 v[2:3], s[0:1]
	s_mov_b64 s[48:49], exec
